# GLA output units run on the 224 non-apply workgroups after the mid barrier; ffn2-up conversion given only to the workgroups with one o_gla GEMM tile
# baseline (speedup 1.0000x reference)
.LBB0_874:
	v_writelane_b32 v241, s38, 30
	v_writelane_b32 v241, s39, 31
	s_waitcnt vmcnt(0)
	s_barrier
	s_mov_b64 s[0:1], exec
	v_readlane_b32 s4, v240, 9
	v_readlane_b32 s5, v240, 10
	s_and_b64 s[4:5], s[0:1], s[4:5]
	s_mov_b64 exec, s[4:5]
	s_cbranch_execz .LBB0_926
	s_mov_b32 s99, 6
	s_branch .Lmybar

.Lb224_skip:
	s_mov_b64 exec, s[8:9]
	s_barrier
	s_sub_i32 s3, s2, 32
	s_lshl_b32 s0, s3, 3
	s_add_i32 s8, s57, s0
	s_waitcnt vmcnt(0)
	v_readlane_b32 s60, v240, 1
	v_readlane_b32 s61, v240, 2
	v_readlane_b32 s62, v240, 3
	v_readlane_b32 s63, v240, 4
	v_readlane_b32 s64, v240, 5
	v_readlane_b32 s65, v240, 6
	v_readlane_b32 s66, v240, 7
	v_readlane_b32 s67, v240, 8
	s_add_i32 s9, s80, 0xffffff00
	s_sub_i32 s8, s8, 0x100
	s_sub_i32 s9, s9, 0x100
	s_mul_i32 s4, s57, 0x2100
	v_lshrrev_b32_e32 v55, 3, v146
	v_and_b32_e32 v56, 7, v146
	v_mul_u32_u24_e32 v44, 0x84, v55
	v_lshl_add_u32 v44, v56, 4, v44
	v_add_u32_e32 v44, s4, v44
	v_add_u32_e32 v45, 0x420, v44
	v_add_u32_e32 v46, 0x840, v44
	v_add_u32_e32 v47, 0xc60, v44
	v_add_u32_e32 v48, 0x1080, v44
	v_add_u32_e32 v49, 0x14a0, v44
	v_add_u32_e32 v50, 0x18c0, v44
	v_add_u32_e32 v51, 0x1ce0, v44
	v_mul_u32_u24_e32 v52, 0x420, v56
	v_lshl_add_u32 v52, v55, 2, v52
	v_add_u32_e32 v52, s4, v52
	v_lshrrev_b32_e32 v55, 3, v146
	v_and_b32_e32 v56, 7, v146
	s_mov_b32 s4, 0x5800
	v_mul_lo_u32 v53, v55, s4
	v_lshl_add_u32 v53, v56, 4, v53
	s_mov_b32 s4, 0x1000
	v_mul_lo_u32 v54, v55, s4
	v_lshl_add_u32 v54, v56, 4, v54
	s_mov_b32 s0, s8
	s_cmp_ge_u32 s0, 0x2c00
	s_cbranch_scc1 .Lcv_done_p7up
	s_lshr_b32 s10, s0, 5
	s_mul_i32 s10, s10, 0x1746
	s_lshr_b32 s10, s10, 16
	s_mul_i32 s11, s10, 352
	s_sub_u32 s11, s0, s11
	s_lshl_b32 s5, s11, 5
	s_lshr_b32 s6, s5, 8
	s_lshl_b32 s6, s6, 7
	s_and_b32 s7, s5, 0x7f
	s_add_u32 s6, s6, s7
	s_bitcmp1_b32 s5, 7
	s_mov_b32 s5, s6
	s_cselect_b32 s12, s64, s62
	s_cselect_b32 s13, s65, s63
	s_mul_i32 s6, s10, 0x160000
	s_lshl_b32 s5, s5, 2
	s_add_u32 s6, s6, s5
	s_add_u32 s12, s12, s6
	s_addc_u32 s13, s13, 0
	global_load_dwordx4 v[64:67], v53, s[12:13] nt
	s_add_u32 s12, s12, 0x2c000
	s_addc_u32 s13, s13, 0
	global_load_dwordx4 v[68:71], v53, s[12:13] nt
	s_add_u32 s12, s12, 0x2c000
	s_addc_u32 s13, s13, 0
	global_load_dwordx4 v[72:75], v53, s[12:13] nt
	s_add_u32 s12, s12, 0x2c000
	s_addc_u32 s13, s13, 0
	global_load_dwordx4 v[76:79], v53, s[12:13] nt
	s_add_u32 s12, s12, 0x2c000
	s_addc_u32 s13, s13, 0
	global_load_dwordx4 v[80:83], v53, s[12:13] nt
	s_add_u32 s12, s12, 0x2c000
	s_addc_u32 s13, s13, 0
	global_load_dwordx4 v[84:87], v53, s[12:13] nt
	s_add_u32 s12, s12, 0x2c000
	s_addc_u32 s13, s13, 0
	global_load_dwordx4 v[88:91], v53, s[12:13] nt
	s_add_u32 s12, s12, 0x2c000
	s_addc_u32 s13, s13, 0
	global_load_dwordx4 v[92:95], v53, s[12:13] nt
	s_add_u32 s1, s0, s9
	s_cmp_ge_u32 s1, 0x2c00
	s_cbranch_scc1 .Lcv_only1_p7up
	s_lshr_b32 s10, s1, 5
	s_mul_i32 s10, s10, 0x1746
	s_lshr_b32 s10, s10, 16
	s_mul_i32 s11, s10, 352
	s_sub_u32 s11, s1, s11
	s_lshl_b32 s5, s11, 5
	s_lshr_b32 s6, s5, 8
	s_lshl_b32 s6, s6, 7
	s_and_b32 s7, s5, 0x7f
	s_add_u32 s6, s6, s7
	s_bitcmp1_b32 s5, 7
	s_mov_b32 s5, s6
	s_cselect_b32 s12, s64, s62
	s_cselect_b32 s13, s65, s63
	s_mul_i32 s6, s10, 0x160000
	s_lshl_b32 s5, s5, 2
	s_add_u32 s6, s6, s5
	s_add_u32 s12, s12, s6
	s_addc_u32 s13, s13, 0
	global_load_dwordx4 v[96:99], v53, s[12:13] nt
	s_add_u32 s12, s12, 0x2c000
	s_addc_u32 s13, s13, 0
	global_load_dwordx4 v[100:103], v53, s[12:13] nt
	s_add_u32 s12, s12, 0x2c000
	s_addc_u32 s13, s13, 0
	global_load_dwordx4 v[104:107], v53, s[12:13] nt
	s_add_u32 s12, s12, 0x2c000
	s_addc_u32 s13, s13, 0
	global_load_dwordx4 v[108:111], v53, s[12:13] nt
	s_add_u32 s12, s12, 0x2c000
	s_addc_u32 s13, s13, 0
	global_load_dwordx4 v[112:115], v53, s[12:13] nt
	s_add_u32 s12, s12, 0x2c000
	s_addc_u32 s13, s13, 0
	global_load_dwordx4 v[116:119], v53, s[12:13] nt
	s_add_u32 s12, s12, 0x2c000
	s_addc_u32 s13, s13, 0
	global_load_dwordx4 v[120:123], v53, s[12:13] nt
	s_add_u32 s12, s12, 0x2c000
	s_addc_u32 s13, s13, 0
	global_load_dwordx4 v[124:127], v53, s[12:13] nt
	s_waitcnt vmcnt(8)
	s_branch .Lcv_procA_p7up
